# GQA attention tiles also staged by LDS-DMA into a 3-stage ring (both attention loops now free of register staging)
# speedup vs baseline: 1.0152x; 1.0052x over previous
; DI int opaque_tid() { int t = threadIdx.x; asm volatile("" : "+v"(t)); return t; }
; DI void flash_pass_q2(f32x16 (&o)[2][2], const u16* __restrict__ Qp0, const u16* __restrict__ Qp1,
;                       const u16* __restrict__ Kb, int ldk, const u16* __restrict__ Vt, int S, int ntiles, char* lds) {
;   const int tid = opaque_tid(), lane = tid & 63;
;   const int h = lane >> 5, r = lane & 31;
;   bf16x8 q[2][4];
; #pragma unroll
;   for (int ks = 0; ks < 4; ++ks) {
;     q[0][ks] = *(const bf16x8*)(Qp0 + ks * 16 + h * 8);
;     q[1][ks] = *(const bf16x8*)(Qp1 + ks * 16 + h * 8);
;   }
; #pragma unroll
;   for (int hq = 0; hq < 2; ++hq)
; #pragma unroll
;     for (int mv = 0; mv < 2; ++mv)
; #pragma unroll
;       for (int i = 0; i < 16; ++i) o[hq][mv][i] = 0.f;
;   float m_run[2] = {-INFINITY, -INFINITY}, l_run[2] = {0.f, 0.f};
;   const int lr = tid >> 3, lc = tid & 7;
;   const int wsw = lr * 128 + ((lc ^ ((lr >> 1) & 7)) << 4);
;   u32x4 rk, rv;
;   auto gload = [&](int ti) {
;     const size_t key0 = (size_t)ti * 64;
;     rk = *(const u32x4*)(Kb + (key0 + lr) * ldk + lc * 8);
;     rv = *(const u32x4*)(Vt + (size_t)lr * S + key0 + lc * 8);
;   };
;   auto swrite = [&](int st) {
;     char* ks_ = lds + st * ATT_STAGE;
;     *(u32x4*)(ks_ + wsw) = rk;
;     *(u32x4*)(ks_ + 8192 + wsw) = rv;
;   };
;   const int pr = (r & 0x13) | ((r & 4) << 1) | ((r & 8) >> 1);
;   const int ksw = (pr >> 1) & 7;
;   const int vsw = (r >> 1) & 7;
;   __syncthreads();
;   gload(0);
;   swrite(0);
;   if (ntiles > 1) gload(1);
;   __syncthreads();
.LBB0_275:
	s_andn2_saveexec_b64 s[18:19], s[18:19]
	v_ashrrev_i32_e32 v2, 8, v0
	v_lshrrev_b32_e32 v8, 6, v0
	v_and_b32_e32 v3, 63, v0
	s_or_b64 s[16:17], s[16:17], exec
	s_or_b64 exec, exec, s[18:19]
	v_lshlrev_b32_e32 v0, 14, v2
	v_lshl_add_u32 v4, v2, 11, v220
	v_cmp_gt_i32_e32 vcc, 2, v2
	v_lshlrev_b32_e32 v2, 8, v3
	v_mov_b64_e32 v[10:11], s[2:3]
	v_cndmask_b32_e32 v0, v4, v0, vcc
	s_movk_i32 s20, 0x500
	v_add3_u32 v196, v226, v2, v0
	v_mad_i64_i32 v[2:3], s[18:19], v0, s96, 0
	v_mad_i64_i32 v[160:161], s[18:19], v0, s96, v[10:11]
	v_mad_i64_i32 v[4:5], s[18:19], v0, s20, 0
	v_readlane_b32 s18, v254, 1
	v_readlane_b32 s19, v254, 2
	v_and_b32_e32 v9, 3, v8
	v_cndmask_b32_e32 v12, v221, v222, vcc
	v_mov_b64_e32 v[6:7], s[18:19]
	s_xor_b64 s[16:17], s[16:17], -1
	v_mad_i64_i32 v[6:7], s[18:19], v0, s20, v[6:7]
	v_ashrrev_i32_e32 v197, 31, v196
	v_mad_i64_i32 v[162:163], s[18:19], v196, s96, v[10:11]
	v_lshlrev_b32_e32 v198, 7, v9
	v_lshrrev_b32_e32 v185, 6, v12
	s_waitcnt vmcnt(9)
	v_cndmask_b32_e64 v176, 11, 14, vcc
	s_and_saveexec_b64 s[18:19], s[16:17]
	s_xor_b64 s[16:17], exec, s[18:19]
	s_cbranch_execz .LBB0_291
	v_lshlrev_b32_e32 v0, 8, v9
	v_lshl_add_u64 v[10:11], v[162:163], 0, v[0:1]
	v_lshlrev_b32_e32 v0, 5, v9
	v_and_b32_e32 v9, 64, v0
	v_lshlrev_b32_e32 v0, 1, v9
	v_lshl_add_u64 v[12:13], v[160:161], 0, v[0:1]
	v_or_b32_e32 v0, 0x200, v9
	v_mov_b32_e32 v9, v204
	v_mov_b32_e32 v15, v1
	v_bfe_u32 v24, v9, 5, 1
	v_lshlrev_b32_e32 v14, 4, v24
	v_lshl_add_u64 v[10:11], v[10:11], 0, v[14:15]
	v_ashrrev_i32_e32 v18, 3, v9
	v_lshlrev_b32_e32 v25, 4, v9
	v_lshlrev_b32_e32 v0, v176, v0
	global_load_dwordx4 v[168:171], v[10:11], off offset:2048
	global_load_dwordx4 v[164:167], v[10:11], off offset:2080
	global_load_dwordx4 v[172:175], v[10:11], off offset:2176
	global_load_dwordx4 v[160:163], v[10:11], off offset:2208
	global_load_dwordx4 v[156:159], v[10:11], off offset:2112
	global_load_dwordx4 v[148:151], v[10:11], off offset:2144
	global_load_dwordx4 v[152:155], v[10:11], off offset:2240
	global_load_dwordx4 v[144:147], v[10:11], off offset:2272
	v_ashrrev_i32_e32 v19, 31, v18
	v_mad_i64_i32 v[10:11], s[18:19], v18, s96, v[12:13]
	v_and_b32_e32 v12, 0x70, v25
	v_mov_b32_e32 v13, v1
	v_lshlrev_b32_e32 v0, 1, v0
	v_lshl_add_u64 v[20:21], v[10:11], 0, v[12:13]
	v_lshlrev_b64 v[10:11], v176, v[18:19]
	v_lshl_add_u64 v[6:7], v[6:7], 0, v[0:1]
	v_lshlrev_b64 v[22:23], 1, v[10:11]
	v_lshl_add_u64 v[6:7], v[6:7], 0, v[22:23]
	s_barrier
	v_lshl_add_u64 v[6:7], v[6:7], 0, v[12:13]
	global_load_dwordx4 v[10:13], v[20:21], off offset:3072
	global_load_dwordx4 v[14:17], v[6:7], off
	v_add_co_u32_e32 v20, vcc, s97, v20
	v_lshlrev_b32_e32 v19, 1, v9
	s_nop 0
	v_addc_co_u32_e32 v21, vcc, 0, v21, vcc
	global_load_dwordx4 v[176:179], v[20:21], off offset:3072
	global_load_dwordx4 v[180:183], v[6:7], off offset:128
	v_lshrrev_b32_e32 v20, 1, v9
	v_and_b32_e32 v7, 19, v9
	v_and_b32_e32 v19, 8, v19
	v_and_b32_e32 v20, 4, v20
	v_lshrrev_b32_e32 v6, 5, v9
	v_bfe_u32 v21, v9, 1, 3
	v_lshlrev_b32_e32 v26, 7, v9
	v_and_b32_e32 v27, 7, v9
	v_lshlrev_b32_e32 v28, 7, v18
	v_xor_b32_e32 v9, v25, v9
	v_or3_b32 v7, v19, v7, v20
	v_and_or_b32 v237, v9, s66, v28
	v_lshrrev_b32_e32 v9, 1, v7
	v_lshlrev_b32_e32 v238, 7, v7
	v_bitop3_b32 v7, v9, v24, 7 bitop3:0x6c
	v_bitop3_b32 v30, v6, v21, 1 bitop3:0x6c
	v_lshlrev_b32_e32 v6, 4, v27
	v_lshlrev_b32_e32 v239, 4, v7
	v_mov_b32_e32 v7, v1
	v_lshl_add_u64 v[4:5], v[4:5], 0, v[6:7]
	v_lshl_add_u64 v[4:5], v[4:5], 0, v[22:23]
	v_readlane_b32 s18, v254, 45
	v_lshl_add_u64 v[4:5], v[4:5], 0, v[0:1]
	v_readlane_b32 s19, v254, 46
	v_and_b32_e32 v0, 2, v8
	v_lshlrev_b32_e32 v0, 6, v0
	v_lshl_add_u64 v[200:201], s[18:19], 0, v[4:5]
	v_mad_i64_i32 v[2:3], s[18:19], v18, s96, v[2:3]
	v_and_b32_e32 v195, 0xf80, v26
	v_or_b32_e32 v25, 2, v24
	v_or_b32_e32 v26, 4, v24
	v_or_b32_e32 v29, 6, v24
	v_lshl_add_u64 v[2:3], v[2:3], 0, v[0:1]
	v_readlane_b32 s18, v254, 47
	v_bitop3_b32 v31, v24, v21, 2 bitop3:0x36
	v_bitop3_b32 v32, v24, v21, 4 bitop3:0x36
	v_bitop3_b32 v21, v24, v21, 6 bitop3:0x36
	v_bitop3_b32 v19, v9, v25, 7 bitop3:0x6c
	v_bitop3_b32 v20, v9, v26, 7 bitop3:0x6c
	v_bitop3_b32 v9, v9, v29, 7 bitop3:0x6c
	v_lshl_add_u64 v[2:3], v[2:3], 0, v[6:7]
	v_readlane_b32 s19, v254, 48
	v_lshlrev_b32_e32 v232, 4, v30
	v_lshlrev_b32_e32 v231, 4, v31
	v_lshlrev_b32_e32 v230, 4, v32
	v_lshlrev_b32_e32 v228, 4, v21
	v_lshlrev_b32_e32 v236, 4, v19
	v_lshlrev_b32_e32 v235, 4, v20
	v_lshlrev_b32_e32 v234, 4, v9
	v_lshl_add_u64 v[202:203], s[18:19], 0, v[2:3]
	v_mov_b32_e32 v0, v1
	v_mov_b32_e32 v2, v1
	s_waitcnt vmcnt(3)
	ds_write_b128 v237, v[10:13]
	s_waitcnt vmcnt(2)
	ds_write_b128 v237, v[14:17] offset:8192
	v_mov_b32_e32 v14, v1
	v_mov_b32_e32 v15, v1
	v_mov_b32_e32 v3, v1
	v_mov_b32_e32 v4, v1
	v_mov_b32_e32 v5, v1
	v_mov_b32_e32 v6, v1
	v_mov_b32_e32 v8, v1
	v_mov_b32_e32 v9, v1
	v_mov_b32_e32 v10, v1
	v_mov_b32_e32 v11, v1
	v_mov_b32_e32 v12, v1
	v_mov_b32_e32 v13, v1
	v_mov_b64_e32 v[30:31], v[14:15]
	v_mov_b64_e32 v[46:47], v[14:15]
	v_mov_b64_e32 v[62:63], v[14:15]
	v_mov_b64_e32 v[78:79], v[14:15]
	s_mov_b32 s22, 1
	v_mov_b32_e32 v229, 0
	v_mov_b32_e32 v233, 0xff800000
	s_mov_b64 s[18:19], 0
	v_mov_b64_e32 v[28:29], v[12:13]
	v_mov_b64_e32 v[26:27], v[10:11]
	v_mov_b64_e32 v[24:25], v[8:9]
	v_mov_b64_e32 v[22:23], v[6:7]
	v_mov_b64_e32 v[20:21], v[4:5]
	v_mov_b64_e32 v[18:19], v[2:3]
	v_mov_b64_e32 v[16:17], v[0:1]
	v_mov_b64_e32 v[44:45], v[12:13]
	v_mov_b64_e32 v[42:43], v[10:11]
	v_mov_b64_e32 v[40:41], v[8:9]
	v_mov_b64_e32 v[38:39], v[6:7]
	v_mov_b64_e32 v[36:37], v[4:5]
	v_mov_b64_e32 v[34:35], v[2:3]
	v_mov_b64_e32 v[32:33], v[0:1]
	v_mov_b64_e32 v[60:61], v[12:13]
	v_mov_b64_e32 v[58:59], v[10:11]
	v_mov_b64_e32 v[56:57], v[8:9]
	v_mov_b64_e32 v[54:55], v[6:7]
	v_mov_b64_e32 v[52:53], v[4:5]
	v_mov_b64_e32 v[50:51], v[2:3]
	v_mov_b64_e32 v[48:49], v[0:1]
	v_mov_b64_e32 v[76:77], v[12:13]
	v_mov_b64_e32 v[74:75], v[10:11]
	v_mov_b64_e32 v[72:73], v[8:9]
	v_mov_b64_e32 v[70:71], v[6:7]
	v_mov_b64_e32 v[68:69], v[4:5]
	v_mov_b64_e32 v[66:67], v[2:3]
	v_mov_b64_e32 v[64:65], v[0:1]
	v_mov_b32_e32 v10, 0xff800000
	v_mov_b32_e32 v0, 0
	s_waitcnt lgkmcnt(0)
	s_barrier
	v_mov_b32_e32 v10, 0
	v_mov_b32_e32 v233, 0
	s_mov_b32 s100, 0x2b800000
	v_add_u32_e32 v249, 0x6000, v237
	s_waitcnt vmcnt(1)
	ds_write_b128 v249, v[176:179]
	s_waitcnt vmcnt(0)
	ds_write_b128 v249, v[180:183] offset:8192
	v_and_b32_e32 v2, 7, v204
	v_bfe_u32 v4, v204, 4, 3
	v_xor_b32_e32 v4, v4, v2
	v_sub_u32_e32 v4, v4, v2
	v_lshlrev_b32_e32 v4, 4, v4
	v_ashrrev_i32_e32 v5, 31, v4
	v_lshl_add_u64 v[202:203], v[202:203], 0, v[4:5]
	v_lshl_add_u64 v[200:201], v[200:201], 0, v[4:5]
	v_readfirstlane_b32 s20, v185
	v_readfirstlane_b32 s101, v204
	s_mov_b32 s23, 0xc000
	s_mov_b32 s21, 0
	s_lshr_b32 s101, s101, 6
	s_lshl_b32 s101, s101, 10
	s_branch .LBB0_280
; DI void flash_pass_q2(f32x16 (&o)[2][2], const u16* __restrict__ Qp0, const u16* __restrict__ Qp1,
;                       const u16* __restrict__ Kb, int ldk, const u16* __restrict__ Vt, int S, int ntiles, char* lds) {
;     ...
;   for (int ti = 0; ti < ntiles; ++ti) {
;     if (ti + 1 < ntiles) {
;       swrite((ti + 1) & 1);
;       if (ti + 2 < ntiles) gload(ti + 2);
;     }
;     const char* st = lds + (ti & 1) * ATT_STAGE;
;     f32x16 s[2][2];
; #pragma unroll
;     for (int hq = 0; hq < 2; ++hq)
; #pragma unroll
;       for (int kb = 0; kb < 2; ++kb)
; #pragma unroll
;         for (int i = 0; i < 16; ++i) s[hq][kb][i] = 0.f;
;     {
;       bf16x8 ka[4], kb_[4];
; #pragma unroll
;       for (int ks = 0; ks < 4; ++ks) {
;         const int co = ((2 * ks + h) ^ ksw) << 4;
;         ka[ks] = *(const bf16x8*)(st + pr * 128 + co);
;         kb_[ks] = *(const bf16x8*)(st + (32 + pr) * 128 + co);
;       }
.LBB0_280:
	s_add_i32 s22, s22, 1
	v_add_u32_e32 v11, s21, v238
	v_add_u32_e32 v248, s21, v195
	v_add_u32_e32 v249, v11, v239
	ds_read_b128 v[2:5], v249
	ds_read_b128 v[6:9], v249 offset:4096
	v_add_u32_e32 v249, v11, v236
	ds_read_b128 v[12:15], v249
	ds_read_b128 v[240:243], v249 offset:4096
	s_cmp_lt_u32 s22, s20
	s_cbranch_scc0 .Lg2_nodmaf
	s_add_u32 m0, s23, s101
	s_nop 0
	global_load_lds_dwordx4 v[202:203], off
	s_add_u32 m0, m0, 0x2000
	v_lshl_add_u64 v[202:203], v[202:203], 0, s[82:83]
	global_load_lds_dwordx4 v[200:201], off
	v_lshl_add_u64 v[200:201], v[200:201], 0, s[4:5]
	s_branch .Lg2_dmadonef

; #define MFMA(a, b, c) __builtin_amdgcn_mfma_f32_32x32x16_bf16((a), (b), (c), 0, 0, 0)
; DI float fexp2(float x) { return __builtin_amdgcn_exp2f(x); }
; DI void flash_pass_q2(f32x16 (&o)[2][2], const u16* __restrict__ Qp0, const u16* __restrict__ Qp1,
;                       const u16* __restrict__ Kb, int ldk, const u16* __restrict__ Vt, int S, int ntiles, char* lds) {
;     ...
;       asm volatile("" ::: "memory");
; #pragma unroll
;       for (int ks = 0; ks < 4; ++ks) {
;         s[0][0] = MFMA(ka[ks], q[0][ks], s[0][0]);
;         s[0][1] = MFMA(kb_[ks], q[0][ks], s[0][1]);
;         s[1][0] = MFMA(ka[ks], q[1][ks], s[1][0]);
;         s[1][1] = MFMA(kb_[ks], q[1][ks], s[1][1]);
;       }
;     }
;     bf16x8 pf[2][2][2];
; #pragma unroll
;     for (int hq = 0; hq < 2; ++hq) {
;       float t[32];
; #pragma unroll
;       for (int i = 0; i < 16; ++i) { t[i] = s[hq][0][i]; t[16 + i] = s[hq][1][i]; }
;       float mx = t[0];
; #pragma unroll
;       for (int e = 1; e < 32; ++e) mx = fmaxf(mx, t[e]);
;       mx = fmaxf(mx, __shfl_xor(mx, 32));
;       if (__builtin_amdgcn_ballot_w64(mx > m_run[hq] + 8.f) != 0ull) {
;         const float m_new = fmaxf(m_run[hq], mx);
;         const float alpha = fexp2(m_run[hq] - m_new);
;         l_run[hq] *= alpha;
;         m_run[hq] = m_new;
; #pragma unroll
;         for (int mv = 0; mv < 2; ++mv)
; #pragma unroll
;           for (int i = 0; i < 16; ++i) o[hq][mv][i] *= alpha;
;       }
;       float ls = 0.f;
; #pragma unroll
;       for (int e = 0; e < 32; ++e) { t[e] = fexp2(t[e] - m_run[hq]); ls += t[e]; }
;       l_run[hq] += ls;
.Lg2_dmadonef:
	v_cmp_eq_u32_e32 vcc, s22, v185
	s_waitcnt lgkmcnt(2)
	v_mfma_f32_32x32x16_bf16 v[128:143], v[2:5], v[168:171], 0
	v_mfma_f32_32x32x16_bf16 v[112:127], v[6:9], v[168:171], 0
	v_mfma_f32_32x32x16_bf16 v[96:111], v[2:5], v[172:175], 0
	v_mfma_f32_32x32x16_bf16 v[80:95], v[6:9], v[172:175], 0
	s_or_b64 s[18:19], vcc, s[18:19]
	v_add_u32_e32 v249, v11, v235
	ds_read_b128 v[2:5], v249
	ds_read_b128 v[6:9], v249 offset:4096
	s_waitcnt lgkmcnt(2)
	v_mfma_f32_32x32x16_bf16 v[128:143], v[12:15], v[164:167], v[128:143]
	v_mfma_f32_32x32x16_bf16 v[112:127], v[240:243], v[164:167], v[112:127]
	v_mfma_f32_32x32x16_bf16 v[96:111], v[12:15], v[160:163], v[96:111]
	v_mfma_f32_32x32x16_bf16 v[80:95], v[240:243], v[160:163], v[80:95]
	v_add_u32_e32 v249, v11, v234
	ds_read_b128 v[12:15], v249
	ds_read_b128 v[240:243], v249 offset:4096
	s_waitcnt lgkmcnt(2)
	v_mfma_f32_32x32x16_bf16 v[128:143], v[2:5], v[156:159], v[128:143]
	v_mfma_f32_32x32x16_bf16 v[112:127], v[6:9], v[156:159], v[112:127]
	v_mfma_f32_32x32x16_bf16 v[96:111], v[2:5], v[152:155], v[96:111]
	v_mfma_f32_32x32x16_bf16 v[80:95], v[6:9], v[152:155], v[80:95]
	v_add_u32_e32 v249, v248, v232
	ds_read_b128 v[2:5], v249 offset:8192
	ds_read_b128 v[6:9], v249 offset:12288
	s_waitcnt lgkmcnt(2)
	v_mfma_f32_32x32x16_bf16 v[128:143], v[12:15], v[148:151], v[128:143]
	v_mfma_f32_32x32x16_bf16 v[112:127], v[240:243], v[148:151], v[112:127]
	v_mfma_f32_32x32x16_bf16 v[96:111], v[12:15], v[144:147], v[96:111]
	v_mfma_f32_32x32x16_bf16 v[80:95], v[240:243], v[144:147], v[80:95]
	v_add_u32_e32 v249, v248, v231
	ds_read_b128 v[12:15], v249 offset:8192
	ds_read_b128 v[240:243], v249 offset:12288
	s_nop 5
	v_exp_f32_e32 v128, v128
	v_exp_f32_e32 v129, v129
	v_exp_f32_e32 v130, v130
	v_exp_f32_e32 v131, v131
	v_exp_f32_e32 v132, v132
	v_exp_f32_e32 v133, v133
	v_exp_f32_e32 v134, v134
	v_exp_f32_e32 v135, v135
	v_exp_f32_e32 v136, v136
	v_exp_f32_e32 v137, v137
	v_add_f32_e32 v210, v128, v130
	v_add_f32_e32 v246, v129, v131
	v_exp_f32_e32 v138, v138
	v_exp_f32_e32 v139, v139
	v_add_f32_e32 v210, v210, v132
	v_add_f32_e32 v246, v246, v133
	v_exp_f32_e32 v140, v140
	v_exp_f32_e32 v141, v141
	v_add_f32_e32 v210, v210, v134
	v_add_f32_e32 v246, v246, v135
	v_exp_f32_e32 v142, v142
	v_exp_f32_e32 v143, v143
	v_add_f32_e32 v210, v210, v136
	v_add_f32_e32 v246, v246, v137
	v_exp_f32_e32 v112, v112
	v_exp_f32_e32 v113, v113
	v_add_f32_e32 v210, v210, v138
	v_add_f32_e32 v246, v246, v139
	v_exp_f32_e32 v114, v114
	v_exp_f32_e32 v115, v115
	v_add_f32_e32 v210, v210, v140
	v_add_f32_e32 v246, v246, v141
	v_exp_f32_e32 v116, v116
	v_exp_f32_e32 v117, v117
	v_add_f32_e32 v210, v210, v142
	v_add_f32_e32 v246, v246, v143
	v_exp_f32_e32 v118, v118
	v_exp_f32_e32 v119, v119
	v_add_f32_e32 v210, v210, v112
	v_add_f32_e32 v246, v246, v113
	v_exp_f32_e32 v120, v120
	v_exp_f32_e32 v121, v121
	v_add_f32_e32 v210, v210, v114
	v_add_f32_e32 v246, v246, v115
	v_exp_f32_e32 v122, v122
	v_exp_f32_e32 v123, v123
	v_add_f32_e32 v210, v210, v116
	v_add_f32_e32 v246, v246, v117
	v_exp_f32_e32 v124, v124
	v_exp_f32_e32 v125, v125
	v_add_f32_e32 v210, v210, v118
	v_add_f32_e32 v246, v246, v119
	v_exp_f32_e32 v126, v126
	v_exp_f32_e32 v127, v127
	v_add_f32_e32 v210, v210, v120
	v_add_f32_e32 v246, v246, v121
	v_add_f32_e32 v210, v210, v122
	v_add_f32_e32 v246, v246, v123
	v_add_f32_e32 v210, v210, v124
	v_add_f32_e32 v246, v246, v125
	v_add_f32_e32 v210, v210, v126
	v_add_f32_e32 v246, v246, v127
	v_add_f32_e32 v210, v210, v246
	v_cmp_lt_f32_e32 vcc, 0x5d800000, v210
	s_cbranch_vccnz .Lg3_ovf0
	v_cmp_gt_f32_e32 vcc, s100, v210
	s_cbranch_vccnz .Lg3_unf0
; #define MFMA(a, b, c) __builtin_amdgcn_mfma_f32_32x32x16_bf16((a), (b), (c), 0, 0, 0)
; DI float fexp2(float x) { return __builtin_amdgcn_exp2f(x); }
; DI void flash_pass_q2(f32x16 (&o)[2][2], const u16* __restrict__ Qp0, const u16* __restrict__ Qp1,
;                       const u16* __restrict__ Kb, int ldk, const u16* __restrict__ Vt, int S, int ntiles, char* lds) {
;     ...
;       float ls = 0.f;
; #pragma unroll
;       for (int e = 0; e < 32; ++e) { t[e] = fexp2(t[e] - m_run[hq]); ls += t[e]; }
;       l_run[hq] += ls;
; #pragma unroll
;       for (int kb = 0; kb < 2; ++kb)
; #pragma unroll
;         for (int c2 = 0; c2 < 2; ++c2) {
;           const int e0 = kb * 16 + c2 * 8;
;           u32x4 pw = {pk_bf16(t[e0], t[e0 + 1]), pk_bf16(t[e0 + 2], t[e0 + 3]), pk_bf16(t[e0 + 4], t[e0 + 5]), pk_bf16(t[e0 + 6], t[e0 + 7])};
;           pf[hq][kb][c2] = __builtin_bit_cast(bf16x8, pw);
;         }
;     }
;     bf16x8 vf[2][2][2];
; #pragma unroll
;     for (int kb = 0; kb < 2; ++kb)
; #pragma unroll
;       for (int c2 = 0; c2 < 2; ++c2) {
;         const int co = ((4 * kb + 2 * c2 + h) ^ vsw) << 4;
; #pragma unroll
;         for (int mv = 0; mv < 2; ++mv) vf[kb][c2][mv] = *(const bf16x8*)(st + 8192 + (mv * 32 + r) * 128 + co);
;       }
;     asm volatile("" ::: "memory");
; #pragma unroll
;     for (int kb = 0; kb < 2; ++kb)
; #pragma unroll
;       for (int c2 = 0; c2 < 2; ++c2)
; #pragma unroll
;         for (int mv = 0; mv < 2; ++mv) {
;           o[0][mv] = MFMA(vf[kb][c2][mv], pf[0][kb][c2], o[0][mv]);
;           o[1][mv] = MFMA(vf[kb][c2][mv], pf[1][kb][c2], o[1][mv]);
;         }
;     __syncthreads();
	v_add_f32_e32 v0, v0, v210
	v_cvt_pk_bf16_f32 v128, v128, v129
	v_cvt_pk_bf16_f32 v129, v130, v131
	v_cvt_pk_bf16_f32 v130, v132, v133
	v_cvt_pk_bf16_f32 v131, v134, v135
	v_cvt_pk_bf16_f32 v136, v136, v137
	v_cvt_pk_bf16_f32 v137, v138, v139
	v_cvt_pk_bf16_f32 v138, v140, v141
	v_cvt_pk_bf16_f32 v139, v142, v143
	v_cvt_pk_bf16_f32 v112, v112, v113
	v_cvt_pk_bf16_f32 v113, v114, v115
	v_cvt_pk_bf16_f32 v114, v116, v117
	v_cvt_pk_bf16_f32 v115, v118, v119
	v_cvt_pk_bf16_f32 v120, v120, v121
	v_cvt_pk_bf16_f32 v121, v122, v123
	v_cvt_pk_bf16_f32 v122, v124, v125
	v_cvt_pk_bf16_f32 v123, v126, v127
	s_waitcnt lgkmcnt(0)
	v_mfma_f32_32x32x16_bf16 v[64:79], v[2:5], v[128:131], v[64:79]
	v_mfma_f32_32x32x16_bf16 v[48:63], v[6:9], v[128:131], v[48:63]
	v_mfma_f32_32x32x16_bf16 v[64:79], v[12:15], v[136:139], v[64:79]
	v_mfma_f32_32x32x16_bf16 v[48:63], v[240:243], v[136:139], v[48:63]
	v_exp_f32_e32 v96, v96
	v_exp_f32_e32 v97, v97
	v_exp_f32_e32 v98, v98
	v_exp_f32_e32 v99, v99
	v_exp_f32_e32 v100, v100
	v_exp_f32_e32 v101, v101
	v_exp_f32_e32 v102, v102
	v_exp_f32_e32 v103, v103
	v_exp_f32_e32 v104, v104
	v_exp_f32_e32 v105, v105
	v_add_f32_e32 v210, v96, v98
	v_add_f32_e32 v246, v97, v99
	v_exp_f32_e32 v106, v106
	v_exp_f32_e32 v107, v107
	v_add_f32_e32 v210, v210, v100
	v_add_f32_e32 v246, v246, v101
	v_exp_f32_e32 v108, v108
	v_exp_f32_e32 v109, v109
	v_add_f32_e32 v210, v210, v102
	v_add_f32_e32 v246, v246, v103
	v_exp_f32_e32 v110, v110
	v_exp_f32_e32 v111, v111
	v_add_f32_e32 v210, v210, v104
	v_add_f32_e32 v246, v246, v105
	v_exp_f32_e32 v80, v80
	v_exp_f32_e32 v81, v81
	v_add_f32_e32 v210, v210, v106
	v_add_f32_e32 v246, v246, v107
	v_exp_f32_e32 v82, v82
	v_exp_f32_e32 v83, v83
	v_add_f32_e32 v210, v210, v108
	v_add_f32_e32 v246, v246, v109
	v_exp_f32_e32 v84, v84
	v_exp_f32_e32 v85, v85
	v_add_f32_e32 v210, v210, v110
	v_add_f32_e32 v246, v246, v111
	v_exp_f32_e32 v86, v86
	v_exp_f32_e32 v87, v87
	v_add_f32_e32 v210, v210, v80
	v_add_f32_e32 v246, v246, v81
	v_exp_f32_e32 v88, v88
	v_exp_f32_e32 v89, v89
	v_add_f32_e32 v210, v210, v82
	v_add_f32_e32 v246, v246, v83
	v_exp_f32_e32 v90, v90
	v_exp_f32_e32 v91, v91
	v_add_f32_e32 v210, v210, v84
	v_add_f32_e32 v246, v246, v85
	v_exp_f32_e32 v92, v92
	v_exp_f32_e32 v93, v93
	v_add_f32_e32 v210, v210, v86
	v_add_f32_e32 v246, v246, v87
	v_exp_f32_e32 v94, v94
	v_exp_f32_e32 v95, v95
	v_add_f32_e32 v210, v210, v88
	v_add_f32_e32 v246, v246, v89
	v_add_f32_e32 v210, v210, v90
	v_add_f32_e32 v246, v246, v91
	v_add_f32_e32 v210, v210, v92
	v_add_f32_e32 v246, v246, v93
	v_add_f32_e32 v210, v210, v94
	v_add_f32_e32 v246, v246, v95
	v_add_f32_e32 v210, v210, v246
	v_cmp_lt_f32_e32 vcc, 0x5d800000, v210
	s_cbranch_vccnz .Lg3_ovf1
	v_cmp_gt_f32_e32 vcc, s100, v210
	s_cbranch_vccnz .Lg3_unf1
	v_add_f32_e32 v229, v229, v210
	v_cvt_pk_bf16_f32 v96, v96, v97
	v_cvt_pk_bf16_f32 v97, v98, v99
	v_cvt_pk_bf16_f32 v98, v100, v101
	v_cvt_pk_bf16_f32 v99, v102, v103
	v_cvt_pk_bf16_f32 v104, v104, v105
	v_cvt_pk_bf16_f32 v105, v106, v107
	v_cvt_pk_bf16_f32 v106, v108, v109
	v_cvt_pk_bf16_f32 v107, v110, v111
	v_cvt_pk_bf16_f32 v80, v80, v81
	v_cvt_pk_bf16_f32 v81, v82, v83
	v_cvt_pk_bf16_f32 v82, v84, v85
	v_cvt_pk_bf16_f32 v83, v86, v87
	v_cvt_pk_bf16_f32 v88, v88, v89
	v_cvt_pk_bf16_f32 v89, v90, v91
	v_cvt_pk_bf16_f32 v90, v92, v93
	v_cvt_pk_bf16_f32 v91, v94, v95
	v_mfma_f32_32x32x16_bf16 v[32:47], v[2:5], v[96:99], v[32:47]
	v_mfma_f32_32x32x16_bf16 v[16:31], v[6:9], v[96:99], v[16:31]
	v_add_u32_e32 v249, v248, v230
	ds_read_b128 v[2:5], v249 offset:8192
	ds_read_b128 v[6:9], v249 offset:12288
	v_mfma_f32_32x32x16_bf16 v[32:47], v[12:15], v[104:107], v[32:47]
	v_mfma_f32_32x32x16_bf16 v[16:31], v[240:243], v[104:107], v[16:31]
	v_add_u32_e32 v249, v248, v228
	ds_read_b128 v[12:15], v249 offset:8192
	ds_read_b128 v[240:243], v249 offset:12288
	s_waitcnt lgkmcnt(2)
	v_mfma_f32_32x32x16_bf16 v[64:79], v[2:5], v[112:115], v[64:79]
	v_mfma_f32_32x32x16_bf16 v[48:63], v[6:9], v[112:115], v[48:63]
	v_mfma_f32_32x32x16_bf16 v[32:47], v[2:5], v[80:83], v[32:47]
	v_mfma_f32_32x32x16_bf16 v[16:31], v[6:9], v[80:83], v[16:31]
	s_waitcnt lgkmcnt(0)
	v_mfma_f32_32x32x16_bf16 v[64:79], v[12:15], v[120:123], v[64:79]
	v_mfma_f32_32x32x16_bf16 v[48:63], v[240:243], v[120:123], v[48:63]
	v_mfma_f32_32x32x16_bf16 v[32:47], v[12:15], v[88:91], v[32:47]
	v_mfma_f32_32x32x16_bf16 v[16:31], v[240:243], v[88:91], v[16:31]
	s_add_u32 s29, s21, s23
	s_mov_b32 s23, s21
	s_sub_u32 s21, 0x12000, s29
	v_mov_b32_e32 v14, s21
	s_waitcnt vmcnt(2)
	s_waitcnt lgkmcnt(0)
	s_barrier
	s_andn2_b64 exec, exec, s[18:19]
	s_mov_b32 s100, 0
	s_cbranch_execnz .LBB0_280
	v_readfirstlane_b32 s101, v204
	s_nop 0
	s_lshr_b32 s101, s101, 8
	s_branch .LBB0_286

; #define MFMA(a, b, c) __builtin_amdgcn_mfma_f32_32x32x16_bf16((a), (b), (c), 0, 0, 0)
; DI void flash_pass_q2(f32x16 (&o)[2][2], const u16* __restrict__ Qp0, const u16* __restrict__ Qp1,
;                       const u16* __restrict__ Kb, int ldk, const u16* __restrict__ Vt, int S, int ntiles, char* lds) {
;     ...
;       bf16x8 ka[4], kb_[4];
; #pragma unroll
;       for (int ks = 0; ks < 4; ++ks) {
;         const int co = ((2 * ks + h) ^ ksw) << 4;
;         ka[ks] = *(const bf16x8*)(st + pr * 128 + co);
;         kb_[ks] = *(const bf16x8*)(st + (32 + pr) * 128 + co);
;       }
;       asm volatile("" ::: "memory");
; #pragma unroll
;       for (int ks = 0; ks < 4; ++ks) {
;         s[0][0] = MFMA(ka[ks], q[0][ks], s[0][0]);
;         s[0][1] = MFMA(kb_[ks], q[0][ks], s[0][1]);
;         s[1][0] = MFMA(ka[ks], q[1][ks], s[1][0]);
;         s[1][1] = MFMA(kb_[ks], q[1][ks], s[1][1]);
;       }
.Lg2_dmadone:
	v_cmp_eq_u32_e32 vcc, s22, v185
	s_waitcnt lgkmcnt(2)
	v_mfma_f32_32x32x16_bf16 v[128:143], v[2:5], v[168:171], 0
	v_mfma_f32_32x32x16_bf16 v[112:127], v[6:9], v[168:171], 0
	v_mfma_f32_32x32x16_bf16 v[96:111], v[2:5], v[172:175], 0
	v_mfma_f32_32x32x16_bf16 v[80:95], v[6:9], v[172:175], 0
	s_or_b64 s[18:19], vcc, s[18:19]
	v_add_u32_e32 v249, v11, v235
	ds_read_b128 v[2:5], v249
	ds_read_b128 v[6:9], v249 offset:4096
	s_waitcnt lgkmcnt(2)
	v_mfma_f32_32x32x16_bf16 v[128:143], v[12:15], v[164:167], v[128:143]
	v_mfma_f32_32x32x16_bf16 v[112:127], v[240:243], v[164:167], v[112:127]
	v_mfma_f32_32x32x16_bf16 v[96:111], v[12:15], v[160:163], v[96:111]
	v_mfma_f32_32x32x16_bf16 v[80:95], v[240:243], v[160:163], v[80:95]
	v_add_u32_e32 v249, v11, v234
	ds_read_b128 v[12:15], v249
	ds_read_b128 v[240:243], v249 offset:4096
	s_waitcnt lgkmcnt(2)
	v_mfma_f32_32x32x16_bf16 v[128:143], v[2:5], v[156:159], v[128:143]
	v_mfma_f32_32x32x16_bf16 v[112:127], v[6:9], v[156:159], v[112:127]
	v_mfma_f32_32x32x16_bf16 v[96:111], v[2:5], v[152:155], v[96:111]
	v_mfma_f32_32x32x16_bf16 v[80:95], v[6:9], v[152:155], v[80:95]
	v_add_u32_e32 v249, v248, v232
	ds_read_b128 v[2:5], v249 offset:8192
	ds_read_b128 v[6:9], v249 offset:12288
	s_waitcnt lgkmcnt(2)
	v_mfma_f32_32x32x16_bf16 v[128:143], v[12:15], v[148:151], v[128:143]
	v_mfma_f32_32x32x16_bf16 v[112:127], v[240:243], v[148:151], v[112:127]
	v_mfma_f32_32x32x16_bf16 v[96:111], v[12:15], v[144:147], v[96:111]
	v_mfma_f32_32x32x16_bf16 v[80:95], v[240:243], v[144:147], v[80:95]
	v_add_u32_e32 v249, v248, v231
	ds_read_b128 v[12:15], v249 offset:8192
	ds_read_b128 v[240:243], v249 offset:12288

; #define MFMA(a, b, c) __builtin_amdgcn_mfma_f32_32x32x16_bf16((a), (b), (c), 0, 0, 0)
; DI float fexp2(float x) { return __builtin_amdgcn_exp2f(x); }
; DI void flash_pass_q2(f32x16 (&o)[2][2], const u16* __restrict__ Qp0, const u16* __restrict__ Qp1,
;                       const u16* __restrict__ Kb, int ldk, const u16* __restrict__ Vt, int S, int ntiles, char* lds) {
;     ...
;       float ls = 0.f;
; #pragma unroll
;       for (int e = 0; e < 32; ++e) { t[e] = fexp2(t[e] - m_run[hq]); ls += t[e]; }
;       l_run[hq] += ls;
; #pragma unroll
;       for (int kb = 0; kb < 2; ++kb)
; #pragma unroll
;         for (int c2 = 0; c2 < 2; ++c2) {
;           const int e0 = kb * 16 + c2 * 8;
;           u32x4 pw = {pk_bf16(t[e0], t[e0 + 1]), pk_bf16(t[e0 + 2], t[e0 + 3]), pk_bf16(t[e0 + 4], t[e0 + 5]), pk_bf16(t[e0 + 6], t[e0 + 7])};
;           pf[hq][kb][c2] = __builtin_bit_cast(bf16x8, pw);
;         }
;     }
;     bf16x8 vf[2][2][2];
; #pragma unroll
;     for (int kb = 0; kb < 2; ++kb)
; #pragma unroll
;       for (int c2 = 0; c2 < 2; ++c2) {
;         const int co = ((4 * kb + 2 * c2 + h) ^ vsw) << 4;
; #pragma unroll
;         for (int mv = 0; mv < 2; ++mv) vf[kb][c2][mv] = *(const bf16x8*)(st + 8192 + (mv * 32 + r) * 128 + co);
;       }
;     asm volatile("" ::: "memory");
; #pragma unroll
;     for (int kb = 0; kb < 2; ++kb)
; #pragma unroll
;       for (int c2 = 0; c2 < 2; ++c2)
; #pragma unroll
;         for (int mv = 0; mv < 2; ++mv) {
;           o[0][mv] = MFMA(vf[kb][c2][mv], pf[0][kb][c2], o[0][mv]);
;           o[1][mv] = MFMA(vf[kb][c2][mv], pf[1][kb][c2], o[1][mv]);
;         }
;     __syncthreads();
.Lg2_sm1:
	v_sub_f32_e32 v96, v96, v233
	v_sub_f32_e32 v97, v97, v233
	v_sub_f32_e32 v98, v98, v233
	v_sub_f32_e32 v99, v99, v233
	v_sub_f32_e32 v100, v100, v233
	v_sub_f32_e32 v101, v101, v233
	v_sub_f32_e32 v102, v102, v233
	v_sub_f32_e32 v103, v103, v233
	v_sub_f32_e32 v104, v104, v233
	v_sub_f32_e32 v105, v105, v233
	v_sub_f32_e32 v106, v106, v233
	v_sub_f32_e32 v107, v107, v233
	v_sub_f32_e32 v108, v108, v233
	v_sub_f32_e32 v109, v109, v233
	v_sub_f32_e32 v110, v110, v233
	v_sub_f32_e32 v111, v111, v233
	v_sub_f32_e32 v80, v80, v233
	v_sub_f32_e32 v81, v81, v233
	v_sub_f32_e32 v82, v82, v233
	v_sub_f32_e32 v83, v83, v233
	v_sub_f32_e32 v84, v84, v233
	v_sub_f32_e32 v85, v85, v233
	v_sub_f32_e32 v86, v86, v233
	v_sub_f32_e32 v87, v87, v233
	v_sub_f32_e32 v88, v88, v233
	v_sub_f32_e32 v89, v89, v233
	v_sub_f32_e32 v90, v90, v233
	v_sub_f32_e32 v91, v91, v233
	v_sub_f32_e32 v92, v92, v233
	v_sub_f32_e32 v93, v93, v233
	v_sub_f32_e32 v94, v94, v233
	v_sub_f32_e32 v95, v95, v233
	v_exp_f32_e32 v96, v96
	v_exp_f32_e32 v97, v97
	v_exp_f32_e32 v98, v98
	v_exp_f32_e32 v99, v99
	v_exp_f32_e32 v100, v100
	v_exp_f32_e32 v101, v101
	v_exp_f32_e32 v102, v102
	v_exp_f32_e32 v103, v103
	v_exp_f32_e32 v104, v104
	v_exp_f32_e32 v105, v105
	v_add_f32_e32 v210, v96, v98
	v_add_f32_e32 v246, v97, v99
	v_exp_f32_e32 v106, v106
	v_exp_f32_e32 v107, v107
	v_add_f32_e32 v210, v210, v100
	v_add_f32_e32 v246, v246, v101
	v_exp_f32_e32 v108, v108
	v_exp_f32_e32 v109, v109
	v_add_f32_e32 v210, v210, v102
	v_add_f32_e32 v246, v246, v103
	v_exp_f32_e32 v110, v110
	v_exp_f32_e32 v111, v111
	v_add_f32_e32 v210, v210, v104
	v_add_f32_e32 v246, v246, v105
	v_exp_f32_e32 v80, v80
	v_exp_f32_e32 v81, v81
	v_add_f32_e32 v210, v210, v106
	v_add_f32_e32 v246, v246, v107
	v_exp_f32_e32 v82, v82
	v_exp_f32_e32 v83, v83
	v_add_f32_e32 v210, v210, v108
	v_add_f32_e32 v246, v246, v109
	v_exp_f32_e32 v84, v84
	v_exp_f32_e32 v85, v85
	v_add_f32_e32 v210, v210, v110
	v_add_f32_e32 v246, v246, v111
	v_exp_f32_e32 v86, v86
	v_exp_f32_e32 v87, v87
	v_add_f32_e32 v210, v210, v80
	v_add_f32_e32 v246, v246, v81
	v_exp_f32_e32 v88, v88
	v_exp_f32_e32 v89, v89
	v_add_f32_e32 v210, v210, v82
	v_add_f32_e32 v246, v246, v83
	v_exp_f32_e32 v90, v90
	v_exp_f32_e32 v91, v91
	v_add_f32_e32 v210, v210, v84
	v_add_f32_e32 v246, v246, v85
	v_exp_f32_e32 v92, v92
	v_exp_f32_e32 v93, v93
	v_add_f32_e32 v210, v210, v86
	v_add_f32_e32 v246, v246, v87
	v_exp_f32_e32 v94, v94
	v_exp_f32_e32 v95, v95
	v_add_f32_e32 v210, v210, v88
	v_add_f32_e32 v246, v246, v89
	v_add_f32_e32 v210, v210, v90
	v_add_f32_e32 v246, v246, v91
	v_add_f32_e32 v210, v210, v92
	v_add_f32_e32 v246, v246, v93
	v_add_f32_e32 v210, v210, v94
	v_add_f32_e32 v246, v246, v95
	v_add_f32_e32 v210, v210, v246
	v_cmp_lt_f32_e32 vcc, 0x5d800000, v210
	s_cbranch_vccnz .Lg2_fix1
	v_add_f32_e32 v229, v229, v210
	v_cvt_pk_bf16_f32 v96, v96, v97
	v_cvt_pk_bf16_f32 v97, v98, v99
	v_cvt_pk_bf16_f32 v98, v100, v101
	v_cvt_pk_bf16_f32 v99, v102, v103
	v_cvt_pk_bf16_f32 v104, v104, v105
	v_cvt_pk_bf16_f32 v105, v106, v107
	v_cvt_pk_bf16_f32 v106, v108, v109
	v_cvt_pk_bf16_f32 v107, v110, v111
	v_cvt_pk_bf16_f32 v80, v80, v81
	v_cvt_pk_bf16_f32 v81, v82, v83
	v_cvt_pk_bf16_f32 v82, v84, v85
	v_cvt_pk_bf16_f32 v83, v86, v87
	v_cvt_pk_bf16_f32 v88, v88, v89
	v_cvt_pk_bf16_f32 v89, v90, v91
	v_cvt_pk_bf16_f32 v90, v92, v93
	v_cvt_pk_bf16_f32 v91, v94, v95
	v_mfma_f32_32x32x16_bf16 v[32:47], v[2:5], v[96:99], v[32:47]
	v_mfma_f32_32x32x16_bf16 v[16:31], v[6:9], v[96:99], v[16:31]
	v_add_u32_e32 v249, v248, v230
	ds_read_b128 v[2:5], v249 offset:8192
	ds_read_b128 v[6:9], v249 offset:12288
	v_mfma_f32_32x32x16_bf16 v[32:47], v[12:15], v[104:107], v[32:47]
	v_mfma_f32_32x32x16_bf16 v[16:31], v[240:243], v[104:107], v[16:31]
	v_add_u32_e32 v249, v248, v228
	ds_read_b128 v[12:15], v249 offset:8192
	ds_read_b128 v[240:243], v249 offset:12288
	s_waitcnt lgkmcnt(2)
	v_mfma_f32_32x32x16_bf16 v[64:79], v[2:5], v[112:115], v[64:79]
	v_mfma_f32_32x32x16_bf16 v[48:63], v[6:9], v[112:115], v[48:63]
	v_mfma_f32_32x32x16_bf16 v[32:47], v[2:5], v[80:83], v[32:47]
	v_mfma_f32_32x32x16_bf16 v[16:31], v[6:9], v[80:83], v[16:31]
	s_waitcnt lgkmcnt(0)
	v_mfma_f32_32x32x16_bf16 v[64:79], v[12:15], v[120:123], v[64:79]
	v_mfma_f32_32x32x16_bf16 v[48:63], v[240:243], v[120:123], v[48:63]
	v_mfma_f32_32x32x16_bf16 v[32:47], v[12:15], v[88:91], v[32:47]
	v_mfma_f32_32x32x16_bf16 v[16:31], v[240:243], v[88:91], v[16:31]
	s_add_u32 s29, s21, s23
	s_mov_b32 s23, s21
	s_sub_u32 s21, 0x12000, s29
	v_mov_b32_e32 v14, s21
	s_waitcnt vmcnt(2)
	s_waitcnt lgkmcnt(0)
	s_barrier
	s_andn2_b64 exec, exec, s[18:19]
	s_cbranch_execnz .Lg3_slow
	v_readfirstlane_b32 s101, v204
	s_nop 0
	s_lshr_b32 s101, s101, 8
	s_branch .LBB0_286
